# MLA fast path scalar control trimmed: tile parity from the index bit, no prefetch-valid flag, compact DMA block (second stage = first + one stage, one vcc setup, range test on the later tile first), l
# baseline (speedup 1.0000x reference)
.Lmla_fast:
	s_and_b32 s8, s30, 3
	s_mulk_i32 s8, 0x6400
	v_add3_u32 v142, s8, v144, v145
	v_add3_u32 v0, s8, v143, v132
	ds_read_b128 v[194:197], v0
	ds_read_b128 v[150:153], v0 offset:32
	ds_read_b128 v[158:161], v0 offset:64
	ds_read_b128 v[162:165], v0 offset:96
	ds_read_b128 v[174:177], v0 offset:128
	ds_read_b128 v[178:181], v0 offset:160
.Lmla_fast_havek:
	s_bitcmp1_b32 s30, 0
	s_cbranch_scc1 .Lmla_fast_nodma
	s_and_b64 vcc, exec, s[36:37]
	s_and_b32 s8, s30, 2
	s_xor_b32 s8, s8, 2
	s_mulk_i32 s8, 0x6400
	s_add_i32 m0, s8, s5
	s_cmp_gt_u32 s30, s13
	s_cbranch_scc1 .Lmla_fast_dtail
	global_load_lds_dwordx4 v66, s[26:27]
	s_add_i32 m0, m0, 0x2000
	v_add_u32_e32 v66, v66, v134
	global_load_lds_dwordx4 v68, s[26:27]
	s_add_i32 m0, m0, 0x2000
	v_add_u32_e32 v68, v68, v136
	global_load_lds_dwordx4 v70, s[26:27]
	v_add_u32_e32 v70, v70, v138
	s_cbranch_vccnz .Lmla_fast_g1d
	s_add_i32 m0, s8, 0x6000
	s_nop 0
	global_load_lds_dwordx4 v72, s[26:27]
	v_add_u32_e32 v72, v72, v140
.Lmla_fast_g1d:
	s_add_i32 s8, s8, 0x6400
	s_add_i32 m0, s8, s5
	s_nop 0
	global_load_lds_dwordx4 v66, s[26:27]
	s_add_i32 m0, m0, 0x2000
	v_add_u32_e32 v66, v66, v134
	global_load_lds_dwordx4 v68, s[26:27]
	s_add_i32 m0, m0, 0x2000
	v_add_u32_e32 v68, v68, v136
	global_load_lds_dwordx4 v70, s[26:27]
	v_add_u32_e32 v70, v70, v138
	s_cbranch_vccnz .Lmla_fast_nodma
	s_add_i32 m0, s8, 0x6000
	s_nop 0
	global_load_lds_dwordx4 v72, s[26:27]
	v_add_u32_e32 v72, v72, v140
	s_branch .Lmla_fast_nodma
.Lmla_fast_dtail:
	s_add_i32 s34, s30, 2
	s_cmp_gt_u32 s34, s14
	s_cbranch_scc1 .Lmla_fast_nodma
	global_load_lds_dwordx4 v66, s[26:27]
	s_add_i32 m0, m0, 0x2000
	v_add_u32_e32 v66, v66, v134
	global_load_lds_dwordx4 v68, s[26:27]
	s_add_i32 m0, m0, 0x2000
	v_add_u32_e32 v68, v68, v136
	global_load_lds_dwordx4 v70, s[26:27]
	v_add_u32_e32 v70, v70, v138
	s_cbranch_vccnz .Lmla_fast_nodma
	s_add_i32 m0, s8, 0x6000
	s_nop 0
	global_load_lds_dwordx4 v72, s[26:27]
	v_add_u32_e32 v72, v72, v140
.Lmla_fast_nodma:
	s_waitcnt lgkmcnt(0)
	v_mfma_f32_32x32x16_bf16 v[50:65], v[194:197], v[74:77], v[234:249]
	ds_read_b128 v[194:197], v0 offset:6656
	v_add_f32_e32 v254, v202, v203
	v_add_f32_e32 v255, v204, v205
	v_add_f32_e32 v254, v254, v206
	v_add_f32_e32 v255, v255, v207
	v_add_f32_e32 v254, v254, v208
	v_add_f32_e32 v255, v255, v209
	v_mfma_f32_32x32x16_bf16 v[50:65], v[150:153], v[78:81], v[50:65]
	ds_read_b128 v[150:153], v0 offset:6688
	v_add_f32_e32 v254, v254, v210
	v_add_f32_e32 v255, v255, v211
	v_add_f32_e32 v254, v254, v212
	v_add_f32_e32 v255, v255, v213
	v_add_f32_e32 v254, v254, v214
	v_add_f32_e32 v255, v255, v215
	v_mfma_f32_32x32x16_bf16 v[50:65], v[158:161], v[82:85], v[50:65]
	ds_read_b128 v[158:161], v0 offset:6720
	v_add_f32_e32 v254, v254, v216
	v_add_f32_e32 v255, v255, v217
	v_add_f32_e32 v254, v254, v218
	v_add_f32_e32 v255, v255, v219
	v_add_f32_e32 v254, v254, v220
	v_mfma_f32_32x32x16_bf16 v[50:65], v[162:165], v[86:89], v[50:65]
	ds_read_b128 v[162:165], v0 offset:6752
	v_add_f32_e32 v255, v255, v221
	v_add_f32_e32 v254, v254, v222
	v_add_f32_e32 v255, v255, v223
	v_add_f32_e32 v254, v254, v224
	v_add_f32_e32 v255, v255, v225
	v_mfma_f32_32x32x16_bf16 v[50:65], v[174:177], v[90:93], v[50:65]
	ds_read_b128 v[174:177], v0 offset:6784
	v_add_f32_e32 v254, v254, v226
	v_add_f32_e32 v255, v255, v227
	v_add_f32_e32 v254, v254, v228
	v_add_f32_e32 v255, v255, v229
	v_add_f32_e32 v254, v254, v230
	v_mfma_f32_32x32x16_bf16 v[50:65], v[178:181], v[94:97], v[50:65]
	ds_read_b128 v[178:181], v0 offset:6816
	v_add_f32_e32 v255, v255, v231
	v_add_f32_e32 v254, v254, v232
	v_add_f32_e32 v255, v255, v233
	v_add_f32_e32 v254, v254, v255
	v_add_f32_e32 v147, v147, v254
	s_waitcnt lgkmcnt(5)
	v_mfma_f32_32x32x16_bf16 v[34:49], v[194:197], v[74:77], v[234:249]
	ds_read_b64_tr_b16 v[126:127], v142 offset:13312
	ds_read_b64_tr_b16 v[128:129], v142 offset:14848
	ds_read_b64_tr_b16 v[124:125], v142 offset:14912
	ds_read_b64_tr_b16 v[122:123], v142 offset:13376
	s_waitcnt lgkmcnt(8)
	v_mfma_f32_32x32x16_bf16 v[34:49], v[150:153], v[78:81], v[34:49]
	ds_read_b64_tr_b16 v[118:119], v142 offset:16384
	ds_read_b64_tr_b16 v[120:121], v142 offset:17920
	ds_read_b64_tr_b16 v[116:117], v142 offset:17984
	ds_read_b64_tr_b16 v[114:115], v142 offset:16448
	s_waitcnt lgkmcnt(11)
	v_mfma_f32_32x32x16_bf16 v[34:49], v[158:161], v[82:85], v[34:49]
	ds_read_b64_tr_b16 v[110:111], v142 offset:19456
	ds_read_b64_tr_b16 v[112:113], v142 offset:20992
	ds_read_b64_tr_b16 v[108:109], v142 offset:21056
	ds_read_b64_tr_b16 v[106:107], v142 offset:19520
	s_waitcnt lgkmcnt(11)
	v_mfma_f32_32x32x16_bf16 v[34:49], v[162:165], v[86:89], v[34:49]
	ds_read_b64_tr_b16 v[102:103], v142 offset:22528
	ds_read_b64_tr_b16 v[104:105], v142 offset:24064
	ds_read_b64_tr_b16 v[100:101], v142 offset:24128
	ds_read_b64_tr_b16 v[98:99], v142 offset:22592
	v_mfma_f32_32x32x16_bf16 v[34:49], v[174:177], v[90:93], v[34:49]
	v_exp_f32_e32 v202, v50
	v_mfma_f32_32x32x16_bf16 v[34:49], v[178:181], v[94:97], v[34:49]
	s_bitcmp0_b32 s30, 0
	s_cbranch_scc1 .Lmla_fast_nostag
	s_waitcnt vmcnt(0) lgkmcnt(0)
	s_barrier

.Lmla_fast_ok:
	v_cvt_pk_bf16_f32 v166, v202, v203
	v_cvt_pk_bf16_f32 v167, v204, v205
	v_cvt_pk_bf16_f32 v168, v206, v207
	v_cvt_pk_bf16_f32 v169, v208, v209
	s_waitcnt lgkmcnt(0)
	s_nop 0
	v_mfma_f32_32x32x16_bf16 v[18:33], v[126:129], v[166:169], v[18:33]
	s_add_i32 s8, s30, 1
	s_and_b32 s8, s8, 3
	s_mulk_i32 s8, 0x6400
	v_add3_u32 v0, s8, v143, v132
	v_add3_u32 v142, s8, v144, v145
	v_mfma_f32_32x32x16_bf16 v[2:17], v[122:125], v[166:169], v[2:17]
	v_cvt_pk_bf16_f32 v170, v210, v211
	v_cvt_pk_bf16_f32 v171, v212, v213
	v_cvt_pk_bf16_f32 v172, v214, v215
	v_cvt_pk_bf16_f32 v173, v216, v217
	v_exp_f32_e32 v218, v34
	v_exp_f32_e32 v219, v35
	v_mfma_f32_32x32x16_bf16 v[18:33], v[118:121], v[170:173], v[18:33]
	v_exp_f32_e32 v220, v36
	v_exp_f32_e32 v221, v37
	ds_read_b128 v[194:197], v0
	ds_read_b128 v[150:153], v0 offset:32
	v_mfma_f32_32x32x16_bf16 v[2:17], v[114:117], v[170:173], v[2:17]
	v_exp_f32_e32 v222, v38
	v_exp_f32_e32 v223, v39
	v_exp_f32_e32 v224, v40
	v_exp_f32_e32 v225, v41
	v_cvt_pk_bf16_f32 v166, v218, v219
	v_cvt_pk_bf16_f32 v167, v220, v221
	v_cvt_pk_bf16_f32 v168, v222, v223
	v_cvt_pk_bf16_f32 v169, v224, v225
	ds_read_b128 v[158:161], v0 offset:64
	ds_read_b128 v[162:165], v0 offset:96
	v_mfma_f32_32x32x16_bf16 v[18:33], v[110:113], v[166:169], v[18:33]
	v_exp_f32_e32 v226, v42
	v_exp_f32_e32 v227, v43
	v_exp_f32_e32 v228, v44
	v_mfma_f32_32x32x16_bf16 v[2:17], v[106:109], v[166:169], v[2:17]
	v_exp_f32_e32 v229, v45
	v_exp_f32_e32 v230, v46
	v_exp_f32_e32 v231, v47
	v_exp_f32_e32 v232, v48
	v_exp_f32_e32 v233, v49
	ds_read_b128 v[174:177], v0 offset:128
	ds_read_b128 v[178:181], v0 offset:160
	v_cvt_pk_bf16_f32 v170, v226, v227
	v_cvt_pk_bf16_f32 v171, v228, v229
	v_cvt_pk_bf16_f32 v172, v230, v231
	v_cvt_pk_bf16_f32 v173, v232, v233
	s_add_i32 s30, s30, 1
	s_add_i32 s31, s31, 64
	v_subrev_u32_e32 v146, 64, v146
	s_cmp_le_u32 s31, s4
	v_mfma_f32_32x32x16_bf16 v[18:33], v[102:105], v[170:173], v[18:33]
	v_mfma_f32_32x32x16_bf16 v[2:17], v[98:101], v[170:173], v[2:17]
	s_cbranch_scc0 .Lmla_fast_generic
	s_branch .Lmla_fast_havek
